# P0 weight transpose: gain loads hoisted beside the tile loads, one counted wait per item; plus pipelined MLA tile path
# baseline (speedup 1.0000x reference)
.LBB0_7:
	s_ashr_i32 s55, s54, 31
	v_mov_b32_e32 v34, 1.0
	ds_write2_b32 v44, v26, v27 offset1:1
	ds_write2_b32 v38, v28, v29 offset1:1
.LBB0_8:
	v_pk_mul_f32 v[38:39], v[30:31], v[34:35] op_sel_hi:[1,0]
	ds_write2_b32 v35, v38, v39 offset1:1
	v_pk_mul_f32 v[34:35], v[32:33], v[34:35] op_sel_hi:[1,0]
	s_mul_i32 s59, s59, s58
	ds_write2_b32 v36, v34, v35 offset1:1
	s_sub_i32 s4, s67, s59
	s_waitcnt lgkmcnt(0)
	s_lshl_b32 s4, s4, 5
	ds_read2_b32 v[38:39], v76 offset0:33 offset1:41
	ds_read2_b32 v[40:41], v76 offset1:8
	ds_read2_b32 v[42:43], v76 offset0:66 offset1:74
	ds_read2_b32 v[44:45], v76 offset0:99 offset1:107
	ds_read2_b32 v[46:47], v76 offset0:132 offset1:140
	ds_read2_b32 v[48:49], v76 offset0:165 offset1:173
	ds_read2_b32 v[50:51], v76 offset0:198 offset1:206
	ds_read2_b32 v[52:53], v76 offset0:231 offset1:239
	s_add_i32 s56, s4, s63
	s_waitcnt lgkmcnt(6)
	v_cvt_pk_bf16_f32 v34, v40, v38
	v_add_u32_e32 v38, s56, v176
	v_mad_i64_i32 v[54:55], s[4:5], v38, s65, 0
	v_lshl_add_u64 v[54:55], v[54:55], 1, s[92:93]
	s_lshl_b64 s[4:5], s[54:55], 1
	v_lshl_add_u64 v[54:55], v[54:55], 0, s[4:5]
	s_waitcnt lgkmcnt(4)
	v_cvt_pk_bf16_f32 v35, v42, v44
	s_waitcnt lgkmcnt(2)
	v_cvt_pk_bf16_f32 v36, v46, v48
	s_waitcnt lgkmcnt(0)
	v_cvt_pk_bf16_f32 v37, v50, v52
	v_lshl_add_u64 v[54:55], v[54:55], 0, v[66:67]
	v_add_u32_e32 v38, s56, v1
	global_store_dwordx4 v[54:55], v[34:37], off
	s_nop 1
	v_cvt_pk_bf16_f32 v34, v41, v39
	v_mad_i64_i32 v[38:39], s[54:55], v38, s65, 0
	v_lshl_add_u64 v[38:39], v[38:39], 1, s[92:93]
	v_lshl_add_u64 v[38:39], v[38:39], 0, s[4:5]
	v_cvt_pk_bf16_f32 v35, v43, v45
	v_cvt_pk_bf16_f32 v36, v47, v49
	v_cvt_pk_bf16_f32 v37, v51, v53
	v_lshl_add_u64 v[38:39], v[38:39], 0, v[66:67]
	ds_read2_b32 v[40:41], v76 offset0:16 offset1:24
	ds_read2_b32 v[42:43], v76 offset0:49 offset1:57
	ds_read2_b32 v[44:45], v76 offset0:82 offset1:90
	ds_read2_b32 v[46:47], v76 offset0:115 offset1:123
	ds_read2_b32 v[48:49], v76 offset0:148 offset1:156
	ds_read2_b32 v[50:51], v76 offset0:181 offset1:189
	ds_read2_b32 v[52:53], v76 offset0:214 offset1:222
	ds_read2_b32 v[54:55], v76 offset0:247 offset1:255
	global_store_dwordx4 v[38:39], v[34:37], off
	v_add_u32_e32 v38, s56, v73
	v_mad_i64_i32 v[38:39], s[54:55], v38, s65, 0
	v_lshl_add_u64 v[38:39], v[38:39], 1, s[92:93]
	v_lshl_add_u64 v[38:39], v[38:39], 0, s[4:5]
	s_waitcnt lgkmcnt(6)
	v_cvt_pk_bf16_f32 v34, v40, v42
	s_waitcnt lgkmcnt(4)
	v_cvt_pk_bf16_f32 v35, v44, v46
	s_waitcnt lgkmcnt(2)
	v_cvt_pk_bf16_f32 v36, v48, v50
	s_waitcnt lgkmcnt(0)
	v_cvt_pk_bf16_f32 v37, v52, v54
	v_lshl_add_u64 v[38:39], v[38:39], 0, v[66:67]
	global_store_dwordx4 v[38:39], v[34:37], off
	v_add_u32_e32 v38, s56, v75
	v_mad_i64_i32 v[38:39], s[54:55], v38, s65, 0
	v_lshl_add_u64 v[38:39], v[38:39], 1, s[92:93]
	v_lshl_add_u64 v[38:39], v[38:39], 0, s[4:5]
	v_cvt_pk_bf16_f32 v34, v41, v43
	v_cvt_pk_bf16_f32 v35, v45, v47
	v_cvt_pk_bf16_f32 v36, v49, v51
	v_cvt_pk_bf16_f32 v37, v53, v55
	v_lshl_add_u64 v[38:39], v[38:39], 0, v[66:67]
	global_store_dwordx4 v[38:39], v[34:37], off
	s_waitcnt lgkmcnt(0)

.LBB0_40:
	s_add_i32 s59, s62, s82
	s_cmpk_lt_i32 s59, 0x4780
	s_cselect_b64 s[54:55], -1, 0
	s_lshr_b32 s57, s60, 5
	v_cvt_f32_u32_e32 v34, s57
	s_sub_i32 s70, 0, s57
	s_abs_i32 s61, s56
	s_ashr_i32 s58, s56, 31
	v_rcp_iflag_f32_e32 v34, v34
	s_nop 0
	v_mul_f32_e32 v34, 0x4f7ffffe, v34
	v_cvt_u32_f32_e32 v34, v34
	s_nop 0
	v_readfirstlane_b32 s71, v34
	s_mul_i32 s70, s70, s71
	s_mul_hi_u32 s70, s71, s70
	s_add_i32 s71, s71, s70
	s_mul_hi_u32 s70, s61, s71
	s_mul_i32 s71, s70, s57
	s_sub_i32 s61, s61, s71
	s_add_i32 s81, s70, 1
	s_sub_i32 s71, s61, s57
	s_cmp_ge_u32 s61, s57
	s_cselect_b32 s70, s81, s70
	s_cselect_b32 s61, s71, s61
	s_add_i32 s71, s70, 1
	s_cmp_ge_u32 s61, s57
	s_cselect_b32 s61, s71, s70
	s_xor_b32 s61, s61, s58
	s_sub_i32 s58, s61, s58
	s_mul_i32 s57, s58, s57
	s_lshl_b32 s58, s58, 6
	v_or_b32_e32 v70, s58, v176
	s_sub_i32 s56, s56, s57
	v_ashrrev_i32_e32 v71, 31, v70
	v_or_b32_e32 v36, 8, v70
	s_lshl_b32 s56, s56, 5
	v_mul_lo_u32 v38, v71, s60
	v_mad_u64_u32 v[34:35], s[70:71], v70, s60, 0
	v_mad_u64_u32 v[36:37], s[70:71], v36, s60, 0
	s_ashr_i32 s57, s56, 31
	v_add_u32_e32 v35, v35, v38
	v_add_u32_e32 v37, v37, v38
	s_lshl_b64 vcc, s[56:57], 2
	v_lshl_add_u64 v[34:35], v[34:35], 2, s[4:5]
	v_lshl_add_u64 v[36:37], v[36:37], 2, s[4:5]
	v_lshl_add_u64 v[34:35], v[34:35], 0, vcc
	v_lshl_add_u64 v[36:37], v[36:37], 0, vcc
	v_lshl_add_u64 v[34:35], v[34:35], 0, v[68:69]
	v_lshl_add_u64 v[36:37], v[36:37], 0, v[68:69]
	global_load_dwordx4 v[62:65], v[34:35], off
	global_load_dwordx4 v[58:61], v[36:37], off
	v_or_b32_e32 v34, 16, v70
	v_or_b32_e32 v36, 24, v70
	v_mad_u64_u32 v[34:35], s[70:71], v34, s60, 0
	v_mad_u64_u32 v[36:37], s[70:71], v36, s60, 0
	v_add_u32_e32 v35, v35, v38
	v_add_u32_e32 v37, v37, v38
	v_lshl_add_u64 v[34:35], v[34:35], 2, s[4:5]
	v_lshl_add_u64 v[36:37], v[36:37], 2, s[4:5]
	v_lshl_add_u64 v[34:35], v[34:35], 0, vcc
	v_lshl_add_u64 v[36:37], v[36:37], 0, vcc
	v_lshl_add_u64 v[34:35], v[34:35], 0, v[68:69]
	v_lshl_add_u64 v[36:37], v[36:37], 0, v[68:69]
	global_load_dwordx4 v[54:57], v[34:35], off
	global_load_dwordx4 v[50:53], v[36:37], off
	v_or_b32_e32 v34, 32, v70
	v_or_b32_e32 v36, 40, v70
	v_mad_u64_u32 v[34:35], s[70:71], v34, s60, 0
	v_mad_u64_u32 v[36:37], s[70:71], v36, s60, 0
	v_add_u32_e32 v35, v35, v38
	v_add_u32_e32 v37, v37, v38
	v_lshl_add_u64 v[34:35], v[34:35], 2, s[4:5]
	v_lshl_add_u64 v[36:37], v[36:37], 2, s[4:5]
	v_lshl_add_u64 v[34:35], v[34:35], 0, vcc
	v_lshl_add_u64 v[36:37], v[36:37], 0, vcc
	v_lshl_add_u64 v[34:35], v[34:35], 0, v[68:69]
	v_lshl_add_u64 v[36:37], v[36:37], 0, v[68:69]
	global_load_dwordx4 v[46:49], v[34:35], off
	global_load_dwordx4 v[42:45], v[36:37], off
	v_or_b32_e32 v34, 48, v70
	v_or_b32_e32 v36, 56, v70
	v_mad_u64_u32 v[34:35], s[70:71], v34, s60, 0
	v_mad_u64_u32 v[36:37], s[60:61], v36, s60, 0
	v_add_u32_e32 v35, v35, v38
	v_add_u32_e32 v37, v37, v38
	v_lshl_add_u64 v[34:35], v[34:35], 2, s[4:5]
	v_lshl_add_u64 v[36:37], v[36:37], 2, s[4:5]
	v_lshl_add_u64 v[34:35], v[34:35], 0, vcc
	v_lshl_add_u64 v[36:37], v[36:37], 0, vcc
	v_lshl_add_u64 v[34:35], v[34:35], 0, v[68:69]
	v_lshl_add_u64 v[36:37], v[36:37], 0, v[68:69]
	global_load_dwordx4 v[38:41], v[34:35], off
	s_nop 0
	global_load_dwordx4 v[34:37], v[36:37], off
	s_cmp_lg_u64 s[88:89], 0
	s_cselect_b32 s70, s88, s4
	s_cselect_b32 s71, s89, s5
	v_or_b32_e32 v88, s58, v176
	v_ashrrev_i32_e32 v89, 31, v88
	v_lshl_add_u64 v[88:89], v[88:89], 2, s[70:71]
	global_load_dword v90, v[88:89], off
	global_load_dword v92, v[88:89], off offset:32
	global_load_dword v94, v[88:89], off offset:64
	global_load_dword v96, v[88:89], off offset:96
	global_load_dword v98, v[88:89], off offset:128
	global_load_dword v100, v[88:89], off offset:160
	global_load_dword v102, v[88:89], off offset:192
	global_load_dword v104, v[88:89], off offset:224
	s_cmpk_gt_i32 s59, 0x477f
	s_cbranch_scc1 .LBB0_74
	s_cmpk_lt_i32 s59, 0x1c00
	s_movk_i32 s64, 0x1c00
	s_cbranch_scc1 .LBB0_50
	s_cmpk_gt_u32 s59, 0x23ff
	s_cbranch_scc0 .LBB0_51
	s_cmpk_gt_u32 s59, 0x263f
	s_cbranch_scc0 .LBB0_52
	s_cmpk_gt_u32 s59, 0x323f
	s_cbranch_scc0 .LBB0_53
	s_cmpk_gt_u32 s59, 0x353f
	s_cbranch_scc0 .LBB0_54
	s_cmpk_gt_u32 s59, 0x377f
	s_cbranch_scc0 .LBB0_55
	s_cmpk_gt_u32 s59, 0x3f7f
	s_cbranch_scc0 .LBB0_56
	s_cmpk_gt_u32 s59, 0x437f
	s_cbranch_scc0 .LBB0_57
	s_add_i32 s57, s59, 0xffffbc80
	s_mov_b64 s[60:61], 0
	s_mov_b64 s[90:91], s[52:53]
	s_mov_b64 s[4:5], s[86:87]
	s_branch .LBB0_58

.LBB0_73:
	s_lshr_b32 s57, s64, 5
	v_cvt_f32_u32_e32 v2, s57
	s_sub_i32 s67, 0, s57
	s_abs_i32 s61, s59
	s_ashr_i32 s60, s59, 31
	v_rcp_iflag_f32_e32 v2, v2
	v_mov_b32_e32 v179, v67
	v_mul_f32_e32 v2, 0x4f7ffffe, v2
	v_cvt_u32_f32_e32 v2, v2
	s_nop 0
	v_readfirstlane_b32 s70, v2
	s_mul_i32 s67, s67, s70
	s_mul_hi_u32 s67, s70, s67
	s_add_i32 s70, s70, s67
	s_mul_hi_u32 s67, s61, s70
	s_mul_i32 s70, s67, s57
	s_sub_i32 s61, s61, s70
	s_add_i32 s71, s67, 1
	s_sub_i32 s70, s61, s57
	s_cmp_ge_u32 s61, s57
	s_cselect_b32 s67, s71, s67
	s_cselect_b32 s61, s70, s61
	s_add_i32 s70, s67, 1
	s_cmp_ge_u32 s61, s57
	s_cselect_b32 s61, s70, s67
	s_xor_b32 s61, s61, s60
	s_sub_i32 s60, s61, s60
	s_mul_i32 s57, s60, s57
	s_lshl_b32 s60, s60, 6
	v_or_b32_e32 v28, s60, v176
	v_mov_b32_e32 v106, v28
	s_sub_i32 s57, s59, s57
	s_ashr_i32 s61, s60, 31
	v_mad_u64_u32 v[2:3], s[70:71], v28, s64, 0
	v_or_b32_e32 v4, 8, v28
	v_or_b32_e32 v10, 16, v28
	v_or_b32_e32 v12, 24, v28
	v_or_b32_e32 v18, 32, v28
	v_or_b32_e32 v20, 40, v28
	v_or_b32_e32 v26, 48, v28
	v_or_b32_e32 v28, 56, v28
	s_lshl_b32 s60, s57, 5
	s_mul_i32 s57, s61, s64
	v_mad_u64_u32 v[4:5], s[70:71], v4, s64, 0
	v_mad_u64_u32 v[10:11], s[70:71], v10, s64, 0
	v_mad_u64_u32 v[12:13], s[70:71], v12, s64, 0
	v_mad_u64_u32 v[18:19], s[70:71], v18, s64, 0
	v_mad_u64_u32 v[20:21], s[70:71], v20, s64, 0
	v_mad_u64_u32 v[26:27], s[70:71], v26, s64, 0
	v_mad_u64_u32 v[28:29], s[70:71], v28, s64, 0
	s_ashr_i32 s61, s60, 31
	v_add_u32_e32 v3, s57, v3
	v_add_u32_e32 v5, s57, v5
	v_add_u32_e32 v11, s57, v11
	v_add_u32_e32 v13, s57, v13
	v_add_u32_e32 v19, s57, v19
	v_add_u32_e32 v21, s57, v21
	v_add_u32_e32 v27, s57, v27
	v_add_u32_e32 v29, s57, v29
	v_lshl_add_u64 v[2:3], v[2:3], 2, s[4:5]
	s_lshl_b64 s[60:61], s[60:61], 2
	v_lshl_add_u64 v[4:5], v[4:5], 2, s[4:5]
	v_lshl_add_u64 v[10:11], v[10:11], 2, s[4:5]
	v_lshl_add_u64 v[12:13], v[12:13], 2, s[4:5]
	v_lshl_add_u64 v[18:19], v[18:19], 2, s[4:5]
	v_lshl_add_u64 v[20:21], v[20:21], 2, s[4:5]
	v_lshl_add_u64 v[26:27], v[26:27], 2, s[4:5]
	v_lshl_add_u64 v[28:29], v[28:29], 2, s[4:5]
	v_lshl_add_u64 v[2:3], v[2:3], 0, s[60:61]
	v_lshl_add_u64 v[4:5], v[4:5], 0, s[60:61]
	v_lshl_add_u64 v[10:11], v[10:11], 0, s[60:61]
	v_lshl_add_u64 v[12:13], v[12:13], 0, s[60:61]
	v_lshl_add_u64 v[18:19], v[18:19], 0, s[60:61]
	v_lshl_add_u64 v[20:21], v[20:21], 0, s[60:61]
	v_lshl_add_u64 v[26:27], v[26:27], 0, s[60:61]
	v_lshl_add_u64 v[28:29], v[28:29], 0, s[60:61]
	v_lshl_add_u64 v[2:3], v[2:3], 0, v[178:179]
	v_lshl_add_u64 v[6:7], v[4:5], 0, v[178:179]
	v_lshl_add_u64 v[10:11], v[10:11], 0, v[178:179]
	v_lshl_add_u64 v[14:15], v[12:13], 0, v[178:179]
	v_lshl_add_u64 v[18:19], v[18:19], 0, v[178:179]
	v_lshl_add_u64 v[22:23], v[20:21], 0, v[178:179]
	v_lshl_add_u64 v[26:27], v[26:27], 0, v[178:179]
	v_lshl_add_u64 v[30:31], v[28:29], 0, v[178:179]
	global_load_dwordx4 v[2:5], v[2:3], off
	s_nop 0
	global_load_dwordx4 v[6:9], v[6:7], off
	s_nop 0
	global_load_dwordx4 v[10:13], v[10:11], off
	s_nop 0
	global_load_dwordx4 v[14:17], v[14:15], off
	s_nop 0
	global_load_dwordx4 v[18:21], v[18:19], off
	s_nop 0
	global_load_dwordx4 v[22:25], v[22:23], off
	s_nop 0
	global_load_dwordx4 v[26:29], v[26:27], off
	s_nop 0
	global_load_dwordx4 v[30:33], v[30:31], off
	s_cmp_lg_u64 s[90:91], 0
	s_cselect_b32 s70, s90, s4
	s_cselect_b32 s71, s91, s5
	v_ashrrev_i32_e32 v107, 31, v106
	v_lshl_add_u64 v[106:107], v[106:107], 2, s[70:71]
	global_load_dword v108, v[106:107], off
	global_load_dword v110, v[106:107], off offset:32
	global_load_dword v112, v[106:107], off offset:64
	global_load_dword v114, v[106:107], off offset:96
	global_load_dword v116, v[106:107], off offset:128
	global_load_dword v118, v[106:107], off offset:160
	global_load_dword v120, v[106:107], off offset:192
	global_load_dword v122, v[106:107], off offset:224
	s_mov_b32 s67, s59
.LBB0_74:
	s_and_b64 vcc, exec, s[54:55]
	s_cbranch_vccz .Lp0_wa0
	s_waitcnt vmcnt(16)
	s_branch .Lp0_wa1

.Lp0_wa1:
	s_cmp_lg_u64 s[88:89], 0
	s_cselect_b64 s[60:61], -1, 0
	s_cmp_eq_u64 s[88:89], 0
	v_mov_b32_e32 v72, 1.0
	v_mov_b32_e32 v74, 1.0
	s_cbranch_scc1 .LBB0_76
	s_ashr_i32 s59, s58, 31
	v_lshl_add_u64 v[70:71], v[70:71], 2, s[88:89]
	v_lshl_add_u64 v[78:79], s[58:59], 0, v[176:177]
	v_mov_b32_e32 v70, v90
	v_lshl_add_u64 v[78:79], v[78:79], 2, s[88:89]
	v_mov_b32_e32 v74, v92
	v_pk_mul_f32 v[62:63], v[62:63], v[70:71] op_sel_hi:[1,0]
	v_pk_mul_f32 v[64:65], v[64:65], v[70:71] op_sel_hi:[1,0]
.LBB0_76:
	ds_write2_b32 v77, v62, v63 offset1:1
	ds_write2_b32 v77, v64, v65 offset0:2 offset1:3
	v_pk_mul_f32 v[62:63], v[58:59], v[74:75] op_sel_hi:[1,0]
	v_add_u32_e32 v59, 0x420, v77
	ds_write2_b32 v59, v62, v63 offset1:1
	v_cndmask_b32_e64 v62, 0, 1, s[60:61]
	v_pk_mul_f32 v[60:61], v[60:61], v[74:75] op_sel_hi:[1,0]
	v_add_u32_e32 v58, 0x428, v77
	v_cmp_ne_u32_e64 s[4:5], 1, v62
	s_andn2_b64 vcc, exec, s[60:61]
	ds_write2_b32 v58, v60, v61 offset1:1
	s_cbranch_vccnz .LBB0_78
	s_ashr_i32 s59, s58, 31
	v_lshl_add_u64 v[60:61], s[58:59], 0, v[176:177]
	v_lshl_add_u64 v[60:61], v[60:61], 2, s[88:89]
	v_mov_b32_e32 v62, v94
	v_mov_b32_e32 v72, v96
	v_pk_mul_f32 v[54:55], v[54:55], v[62:63] op_sel_hi:[1,0]
	v_pk_mul_f32 v[56:57], v[56:57], v[62:63] op_sel_hi:[1,0]
.LBB0_78:
	v_add_u32_e32 v60, 0x840, v77
	ds_write2_b32 v60, v54, v55 offset1:1
	v_pk_mul_f32 v[50:51], v[50:51], v[72:73] op_sel_hi:[1,0]
	v_add_u32_e32 v54, 0xc60, v77
	v_add_u32_e32 v55, 0x848, v77
	ds_write2_b32 v54, v50, v51 offset1:1
	v_pk_mul_f32 v[52:53], v[52:53], v[72:73] op_sel_hi:[1,0]
	v_add_u32_e32 v51, 0xc68, v77
	s_and_b64 vcc, exec, s[4:5]
	ds_write2_b32 v55, v56, v57 offset1:1
	ds_write2_b32 v51, v52, v53 offset1:1
	s_cbranch_vccnz .LBB0_80
	s_ashr_i32 s59, s58, 31
	v_lshl_add_u64 v[52:53], s[58:59], 0, v[176:177]
	v_lshl_add_u64 v[52:53], v[52:53], 2, s[88:89]
	v_mov_b32_e32 v56, v98
	v_mov_b32_e32 v50, v100
	v_pk_mul_f32 v[46:47], v[46:47], v[56:57] op_sel_hi:[1,0]
	v_pk_mul_f32 v[48:49], v[48:49], v[56:57] op_sel_hi:[1,0]
	s_branch .LBB0_81

.LBB0_81:
	v_add_u32_e32 v52, 0x1080, v77
	ds_write2_b32 v52, v46, v47 offset1:1
	v_pk_mul_f32 v[42:43], v[42:43], v[50:51] op_sel_hi:[1,0]
	v_add_u32_e32 v46, 0x14a0, v77
	v_add_u32_e32 v47, 0x1088, v77
	ds_write2_b32 v46, v42, v43 offset1:1
	v_pk_mul_f32 v[44:45], v[44:45], v[50:51] op_sel_hi:[1,0]
	v_add_u32_e32 v43, 0x14a8, v77
	s_and_b64 vcc, exec, s[60:61]
	ds_write2_b32 v47, v48, v49 offset1:1
	ds_write2_b32 v43, v44, v45 offset1:1
	s_cbranch_vccz .LBB0_96
	s_ashr_i32 s59, s58, 31
	v_lshl_add_u64 v[44:45], s[58:59], 0, v[176:177]
	v_lshl_add_u64 v[44:45], v[44:45], 2, s[88:89]
	v_mov_b32_e32 v48, v102
	v_mov_b32_e32 v42, v104
	v_pk_mul_f32 v[38:39], v[38:39], v[48:49] op_sel_hi:[1,0]
	v_pk_mul_f32 v[40:41], v[40:41], v[48:49] op_sel_hi:[1,0]
	s_cbranch_execnz .LBB0_84
.LBB0_83:
	s_ashr_i32 s59, s58, 31
	v_mov_b32_e32 v42, 1.0
.LBB0_84:
	v_add_u32_e32 v44, 0x18c0, v77
	ds_write2_b32 v44, v38, v39 offset1:1
	v_add_u32_e32 v38, 0x18c8, v77
	ds_write2_b32 v38, v40, v41 offset1:1
	v_pk_mul_f32 v[40:41], v[34:35], v[42:43] op_sel_hi:[1,0]
	v_add_u32_e32 v35, 0x1ce0, v77
	ds_write2_b32 v35, v40, v41 offset1:1
	v_pk_mul_f32 v[40:41], v[36:37], v[42:43] op_sel_hi:[1,0]
	v_add_u32_e32 v36, 0x1ce8, v77
	ds_write2_b32 v36, v40, v41 offset1:1
	v_or_b32_e32 v34, s66, v176
	s_waitcnt lgkmcnt(0)
	v_add_u32_e32 v34, s56, v34
	ds_read2_b32 v[40:41], v76 offset0:33 offset1:41
	ds_read2_b32 v[48:49], v76 offset1:8
	ds_read2_b32 v[56:57], v76 offset0:66 offset1:74
	ds_read2_b32 v[70:71], v76 offset0:99 offset1:107
	ds_read2_b32 v[78:79], v76 offset0:132 offset1:140
	ds_read2_b32 v[80:81], v76 offset0:165 offset1:173
	ds_read2_b32 v[82:83], v76 offset0:198 offset1:206
	ds_read2_b32 v[84:85], v76 offset0:231 offset1:239
	v_ashrrev_i32_e32 v37, 31, v34
	v_mul_lo_u32 v37, s94, v37
	v_mul_lo_u32 v39, s95, v34
	v_mad_u64_u32 v[86:87], s[4:5], s94, v34, 0
	v_add3_u32 v87, v87, v37, v39
	v_lshl_add_u64 v[86:87], v[86:87], 1, s[96:97]
	s_lshl_b64 s[4:5], s[58:59], 1
	v_or_b32_e32 v34, s66, v1
	v_lshl_add_u64 v[86:87], v[86:87], 0, s[4:5]
	v_add_u32_e32 v34, s56, v34
	s_waitcnt lgkmcnt(0)
	v_cvt_pk_bf16_f32 v62, v48, v40
	v_cvt_pk_bf16_f32 v63, v56, v70
	v_cvt_pk_bf16_f32 v64, v78, v80
	v_cvt_pk_bf16_f32 v65, v82, v84
	v_lshl_add_u64 v[86:87], v[86:87], 0, v[66:67]
	v_ashrrev_i32_e32 v37, 31, v34
	global_store_dwordx4 v[86:87], v[62:65], off
	v_mul_lo_u32 v37, s94, v37
	v_mul_lo_u32 v39, s95, v34
	v_cvt_pk_bf16_f32 v62, v49, v41
	v_mad_u64_u32 v[40:41], s[58:59], s94, v34, 0
	v_add3_u32 v41, v41, v37, v39
	v_lshl_add_u64 v[40:41], v[40:41], 1, s[96:97]
	v_or_b32_e32 v34, s66, v73
	v_lshl_add_u64 v[40:41], v[40:41], 0, s[4:5]
	v_add_u32_e32 v34, s56, v34
	v_cvt_pk_bf16_f32 v63, v57, v71
	v_cvt_pk_bf16_f32 v64, v79, v81
	v_cvt_pk_bf16_f32 v65, v83, v85
	v_lshl_add_u64 v[40:41], v[40:41], 0, v[66:67]
	ds_read2_b32 v[48:49], v76 offset0:16 offset1:24
	ds_read2_b32 v[56:57], v76 offset0:49 offset1:57
	ds_read2_b32 v[70:71], v76 offset0:82 offset1:90
	ds_read2_b32 v[78:79], v76 offset0:115 offset1:123
	ds_read2_b32 v[80:81], v76 offset0:148 offset1:156
	ds_read2_b32 v[82:83], v76 offset0:181 offset1:189
	ds_read2_b32 v[84:85], v76 offset0:214 offset1:222
	ds_read2_b32 v[86:87], v76 offset0:247 offset1:255
	v_ashrrev_i32_e32 v37, 31, v34
	global_store_dwordx4 v[40:41], v[62:65], off
	v_mul_lo_u32 v37, s94, v37
	v_mul_lo_u32 v39, s95, v34
	v_mad_u64_u32 v[40:41], s[58:59], s94, v34, 0
	v_add3_u32 v41, v41, v37, v39
	v_lshl_add_u64 v[40:41], v[40:41], 1, s[96:97]
	v_or_b32_e32 v34, s66, v75
	v_lshl_add_u64 v[40:41], v[40:41], 0, s[4:5]
	v_add_u32_e32 v34, s56, v34
	s_waitcnt lgkmcnt(6)
	v_cvt_pk_bf16_f32 v62, v48, v56
	s_waitcnt lgkmcnt(4)
	v_cvt_pk_bf16_f32 v63, v70, v78
	s_waitcnt lgkmcnt(2)
	v_cvt_pk_bf16_f32 v64, v80, v82
	s_waitcnt lgkmcnt(0)
	v_cvt_pk_bf16_f32 v65, v84, v86
	v_lshl_add_u64 v[40:41], v[40:41], 0, v[66:67]
	v_ashrrev_i32_e32 v37, 31, v34
	global_store_dwordx4 v[40:41], v[62:65], off
	v_mul_lo_u32 v37, s94, v37
	v_mul_lo_u32 v39, s95, v34
	v_mad_u64_u32 v[40:41], s[56:57], s94, v34, 0
	v_add3_u32 v41, v41, v37, v39
	v_lshl_add_u64 v[40:41], v[40:41], 1, s[96:97]
	v_lshl_add_u64 v[40:41], v[40:41], 0, s[4:5]
	v_cvt_pk_bf16_f32 v62, v49, v57
	v_cvt_pk_bf16_f32 v63, v71, v79
	v_cvt_pk_bf16_f32 v64, v81, v83
	v_cvt_pk_bf16_f32 v65, v85, v87
	v_lshl_add_u64 v[40:41], v[40:41], 0, v[66:67]
	global_store_dwordx4 v[40:41], v[62:65], off
	s_waitcnt lgkmcnt(0)
	s_andn2_b64 vcc, exec, s[54:55]
	s_cbranch_vccnz .LBB0_9
	s_waitcnt vmcnt(4)
	s_ashr_i32 s4, s64, 31
	s_lshr_b32 s4, s4, 27
	s_add_i32 s4, s64, s4
	s_ashr_i32 s58, s4, 5
	s_abs_i32 s4, s58
	v_cvt_f32_u32_e32 v34, s4
	s_sub_i32 s55, 0, s4
	s_abs_i32 s5, s67
	s_xor_b32 s54, s67, s58
	v_rcp_iflag_f32_e32 v34, v34
	s_ashr_i32 s54, s54, 31
	v_mul_f32_e32 v34, 0x4f7ffffe, v34
	v_cvt_u32_f32_e32 v34, v34
	s_nop 0
	v_readfirstlane_b32 s56, v34
	s_mul_i32 s55, s55, s56
	s_mul_hi_u32 s55, s56, s55
	s_add_i32 s56, s56, s55
	s_mul_hi_u32 s55, s5, s56
	s_mul_i32 s56, s55, s4
	s_sub_i32 s5, s5, s56
	s_add_i32 s57, s55, 1
	s_sub_i32 s56, s5, s4
	s_cmp_ge_u32 s5, s4
	s_cselect_b32 s55, s57, s55
	s_cselect_b32 s5, s56, s5
	s_add_i32 s56, s55, 1
	s_cmp_ge_u32 s5, s4
	s_cselect_b32 s4, s56, s55
	s_xor_b32 s4, s4, s54
	s_sub_i32 s59, s4, s54
	s_lshl_b32 s54, s59, 6
	s_cmp_lg_u64 s[90:91], 0
	s_cselect_b64 s[56:57], -1, 0
	s_cmp_eq_u64 s[90:91], 0
	s_cbranch_scc1 .LBB0_97
	v_or_b32_e32 v40, s54, v176
	v_ashrrev_i32_e32 v41, 31, v40
	s_ashr_i32 s55, s54, 31
	v_lshl_add_u64 v[40:41], v[40:41], 2, s[90:91]
	v_lshl_add_u64 v[48:49], s[54:55], 0, v[176:177]
	v_mov_b32_e32 v40, v108
	v_lshl_add_u64 v[48:49], v[48:49], 2, s[90:91]
	v_mov_b32_e32 v34, v110
	v_pk_mul_f32 v[48:49], v[2:3], v[40:41] op_sel_hi:[1,0]
	v_pk_mul_f32 v[40:41], v[4:5], v[40:41] op_sel_hi:[1,0]
	ds_write2_b32 v77, v48, v49 offset1:1
	ds_write2_b32 v77, v40, v41 offset0:2 offset1:3
	s_cbranch_execnz .LBB0_88
.LBB0_87:
	v_mov_b32_e32 v34, 1.0
	ds_write2_b32 v77, v2, v3 offset1:1
	ds_write2_b32 v77, v4, v5 offset0:2 offset1:3
.LBB0_88:
	v_pk_mul_f32 v[40:41], v[6:7], v[34:35] op_sel_hi:[1,0]
	ds_write2_b32 v59, v40, v41 offset1:1
	v_pk_mul_f32 v[40:41], v[8:9], v[34:35] op_sel_hi:[1,0]
	v_cndmask_b32_e64 v34, 0, 1, s[56:57]
	v_cmp_ne_u32_e64 s[4:5], 1, v34
	s_andn2_b64 vcc, exec, s[56:57]
	ds_write2_b32 v58, v40, v41 offset1:1
	s_cbranch_vccnz .LBB0_98
	s_ashr_i32 s55, s54, 31
	v_lshl_add_u64 v[40:41], s[54:55], 0, v[176:177]
	v_lshl_add_u64 v[40:41], v[40:41], 2, s[90:91]
	v_mov_b32_e32 v42, v112
	v_mov_b32_e32 v34, v114
	v_pk_mul_f32 v[40:41], v[10:11], v[42:43] op_sel_hi:[1,0]
	v_pk_mul_f32 v[48:49], v[12:13], v[42:43] op_sel_hi:[1,0]
	ds_write2_b32 v60, v40, v41 offset1:1
	ds_write2_b32 v55, v48, v49 offset1:1
	s_cbranch_execnz .LBB0_91
.LBB0_90:
	v_mov_b32_e32 v34, 1.0
	ds_write2_b32 v60, v10, v11 offset1:1
	ds_write2_b32 v55, v12, v13 offset1:1
.LBB0_91:
	v_pk_mul_f32 v[40:41], v[14:15], v[34:35] op_sel_hi:[1,0]
	ds_write2_b32 v54, v40, v41 offset1:1
	v_pk_mul_f32 v[40:41], v[16:17], v[34:35] op_sel_hi:[1,0]
	s_and_b64 vcc, exec, s[4:5]
	ds_write2_b32 v51, v40, v41 offset1:1
	s_cbranch_vccnz .LBB0_99
	s_ashr_i32 s55, s54, 31
	v_lshl_add_u64 v[40:41], s[54:55], 0, v[176:177]
	v_lshl_add_u64 v[40:41], v[40:41], 2, s[90:91]
	v_mov_b32_e32 v42, v116
	v_mov_b32_e32 v34, v118
	v_pk_mul_f32 v[40:41], v[18:19], v[42:43] op_sel_hi:[1,0]
	v_pk_mul_f32 v[48:49], v[20:21], v[42:43] op_sel_hi:[1,0]
	ds_write2_b32 v52, v40, v41 offset1:1
	ds_write2_b32 v47, v48, v49 offset1:1
	s_cbranch_execnz .LBB0_94
.LBB0_93:
	v_mov_b32_e32 v34, 1.0
	ds_write2_b32 v52, v18, v19 offset1:1
	ds_write2_b32 v47, v20, v21 offset1:1
.LBB0_94:
	v_pk_mul_f32 v[40:41], v[22:23], v[34:35] op_sel_hi:[1,0]
	ds_write2_b32 v46, v40, v41 offset1:1
	v_pk_mul_f32 v[40:41], v[24:25], v[34:35] op_sel_hi:[1,0]
	s_and_b64 vcc, exec, s[4:5]
	ds_write2_b32 v43, v40, v41 offset1:1
	s_cbranch_vccnz .LBB0_100
	s_ashr_i32 s55, s54, 31
	v_lshl_add_u64 v[40:41], s[54:55], 0, v[176:177]
	v_lshl_add_u64 v[40:41], v[40:41], 2, s[90:91]
	v_mov_b32_e32 v42, v120
	v_mov_b32_e32 v34, v122
	v_pk_mul_f32 v[40:41], v[26:27], v[42:43] op_sel_hi:[1,0]
	v_pk_mul_f32 v[42:43], v[28:29], v[42:43] op_sel_hi:[1,0]
	ds_write2_b32 v44, v40, v41 offset1:1
	ds_write2_b32 v38, v42, v43 offset1:1
	s_cbranch_execnz .LBB0_8
	s_branch .LBB0_7
